# code placement: conv-gate K-loop head moved from byte phase 36 to 20 mod 64, the other two loops kept at 16 / 12
# speedup vs baseline: 1.0117x; 1.0117x over previous
; #define PG8_STAGE(bufoff, gbase, voff) do { _Pragma("unroll") for (int _i = 0; _i < 2; ++_i) \
;         __builtin_amdgcn_global_load_lds((const unsigned*)((const char*)(gbase) + (voff)[_i]), (LAS unsigned*)(lds + (bufoff) + ldsw + _i * 8192), 16, 0, 0); } while (0)
; #define PG8_LDA(dst, b, h) do { _Pragma("unroll") for (int m = 0; m < 4; ++m) _Pragma("unroll") for (int k = 0; k < 2; ++k) dst[m][k] = *(const LAS bf16x8*)(lds + PG8_SA(b, h) + aoff + m * 2048 + k * 1024); } while (0)
; #define PG8_LDB(dst, b, h) do { _Pragma("unroll") for (int n = 0; n < 2; ++n) _Pragma("unroll") for (int k = 0; k < 2; ++k) dst[n][k] = *(const LAS bf16x8*)(lds + PG8_SB(b, h) + boff + n * 2048 + k * 1024); } while (0)
; #define PG8_MMA(ai, bj, At, Bt) do { __builtin_amdgcn_s_setprio(1); _Pragma("unroll") for (int m = 0; m < 4; ++m) _Pragma("unroll") for (int n = 0; n < 2; ++n) _Pragma("unroll") for (int k = 0; k < 2; ++k) \
;         acc[ai][bj][m][n] = __builtin_amdgcn_mfma_f32_16x16x32_bf16(Bt[n][k], At[m][k], acc[ai][bj][m][n], 0, 0, 0); __builtin_amdgcn_s_setprio(0); } while (0)
; #define PG8_WAIT_V(n) asm volatile("s_waitcnt vmcnt(" #n ")" ::: "memory")
; #define PG8_WAIT_L(n) asm volatile("s_waitcnt lgkmcnt(" #n ")" ::: "memory")
; #define PG8_BAR __builtin_amdgcn_s_barrier()
; #define PG8_SCHED __builtin_amdgcn_sched_barrier(0)
;     ...
;         const bool has_next = S.next(ui + 1, nxt);
;         const char* nA = has_next ? nxt.A : cA; const char* nB = has_next ? nxt.B : cB;
;         for (int t = 0; t < nt; t += 2) {
;             const bool last = (t == nt - 2);
;             const char* a1 = cA + (size_t)(t + 1) * kstep;
;             const char* a2 = last ? nA : cA + (size_t)(t + 2) * kstep; const char* b2 = last ? nB : cB + (size_t)(t + 2) * kstep;
;             const char* a3 = a2 + kstep; const char* b3 = b2 + kstep;
;             PG8_LDB(B0, 0, 0); PG8_LDB(B1, 0, 1); PG8_SCHED; PG8_LDA(At, 0, 0); PG8_STAGE(PG8_SA(1, 1), a1 + hstepA, voffA);
;             PG8_WAIT_V(8); PG8_WAIT_L(0); PG8_BAR; PG8_MMA(0, 0, At, B0); PG8_MMA(0, 1, At, B1); PG8_BAR; PG8_SCHED;
;             PG8_LDA(At, 0, 1); PG8_STAGE(PG8_SB(0, 0), b2, voffB); PG8_STAGE(PG8_SB(0, 1), b2 + hstepB, voffB); PG8_STAGE(PG8_SA(0, 0), a2, voffA);
;             PG8_WAIT_V(8); PG8_WAIT_L(0); PG8_BAR; PG8_MMA(1, 0, At, B0); PG8_MMA(1, 1, At, B1); PG8_BAR; PG8_SCHED;
.LBB0_158:
	s_mov_b64 s[56:57], s[18:19]
	s_mov_b64 s[16:17], s[2:3]
	v_mov_b32_e32 v228, v128
	s_xor_b64 s[2:3], s[36:37], -1
	v_mov_b32_e32 v128, s57
	s_and_b64 s[0:1], s[36:37], exec
	v_cndmask_b32_e64 v132, v189, v128, s[36:37]
	v_mov_b32_e32 v128, s56
	s_mov_b64 s[68:69], s[8:9]
	s_mov_b64 s[54:55], s[40:41]
	s_cselect_b32 s18, s17, s13
	s_cselect_b32 s19, s16, s12
	v_cndmask_b32_e64 v133, v188, v128, s[36:37]
	s_mov_b32 s8, 0
	s_mov_b64 s[0:1], 0x100
	v_mov_b64_e32 v[128:129], v[202:203]
	v_mov_b64_e32 v[130:131], v[200:201]
	s_nop 0
	s_nop 0
	s_nop 0
	s_nop 0
	s_nop 0
	s_nop 0
	s_nop 0
	s_nop 0
	s_nop 0
	s_nop 0
	s_nop 0
	s_nop 0
.LBB0_159:
	s_add_i32 s38, s8, 2
	s_add_u32 s26, s12, s0
	s_addc_u32 s9, s13, s1
	s_add_i32 s27, 0, 0x10000
	s_cmp_eq_u32 s63, s8
	s_cselect_b32 s9, s18, s9
	s_cselect_b32 s8, s19, s26
	s_cselect_b64 vcc, -1, 0
	s_add_i32 s26, 0, 0x14000
	v_lshl_add_u64 v[150:151], v[188:189], 0, s[0:1]
	v_add_u32_e32 v146, s27, v226
	v_add_u32_e32 v162, s26, v226
	ds_read_b128 v[134:137], v146
	ds_read_b128 v[138:141], v146 offset:1024
	ds_read_b128 v[142:145], v146 offset:2048
	ds_read_b128 v[146:149], v146 offset:3072
	v_cndmask_b32_e32 v205, v151, v132, vcc
	v_cndmask_b32_e32 v204, v150, v133, vcc
	ds_read_b128 v[150:153], v162
	ds_read_b128 v[154:157], v162 offset:1024
	ds_read_b128 v[158:161], v162 offset:2048
	ds_read_b128 v[162:165], v162 offset:3072
	v_lshl_add_u64 v[212:213], s[12:13], 0, v[130:131]
	s_add_i32 m0, s20, 0xc000
	ds_read_b128 v[166:169], v227
	ds_read_b128 v[170:173], v227 offset:1024
	ds_read_b128 v[174:177], v227 offset:2048
	ds_read_b128 v[178:181], v227 offset:3072
	ds_read_b128 v[230:233], v227 offset:4096
	ds_read_b128 v[234:237], v227 offset:5120
	ds_read_b128 v[238:241], v227 offset:6144
	ds_read_b128 v[242:245], v227 offset:7168
	global_load_lds_dwordx4 v[212:213], off
	v_lshl_add_u64 v[212:213], s[12:13], 0, v[128:129]
	s_add_i32 m0, s20, 0xe000
	s_nop 0
	global_load_lds_dwordx4 v[212:213], off
	s_waitcnt vmcnt(8)
	s_waitcnt lgkmcnt(0)
	s_barrier
	s_setprio 1
	s_waitcnt lgkmcnt(0)
	v_mfma_f32_16x16x32_bf16 v[124:127], v[134:137], v[166:169], v[124:127]
	v_mfma_f32_16x16x32_bf16 v[0:3], v[142:145], v[166:169], v[0:3]
	v_mfma_f32_16x16x32_bf16 v[120:123], v[134:137], v[174:177], v[120:123]
	v_mfma_f32_16x16x32_bf16 v[116:119], v[142:145], v[174:177], v[116:119]
	v_mfma_f32_16x16x32_bf16 v[112:115], v[134:137], v[230:233], v[112:115]
	v_mfma_f32_16x16x32_bf16 v[108:111], v[142:145], v[230:233], v[108:111]
	v_mfma_f32_16x16x32_bf16 v[104:107], v[134:137], v[238:241], v[104:107]
	v_mfma_f32_16x16x32_bf16 v[4:7], v[142:145], v[238:241], v[4:7]
	v_mfma_f32_16x16x32_bf16 v[124:127], v[138:141], v[170:173], v[124:127]
	v_mfma_f32_16x16x32_bf16 v[0:3], v[146:149], v[170:173], v[0:3]
	v_mfma_f32_16x16x32_bf16 v[120:123], v[138:141], v[178:181], v[120:123]
	v_mfma_f32_16x16x32_bf16 v[116:119], v[146:149], v[178:181], v[116:119]
	v_mfma_f32_16x16x32_bf16 v[112:115], v[138:141], v[234:237], v[112:115]
	v_mfma_f32_16x16x32_bf16 v[108:111], v[146:149], v[234:237], v[108:111]
	v_mfma_f32_16x16x32_bf16 v[104:107], v[138:141], v[242:245], v[104:107]
	v_mfma_f32_16x16x32_bf16 v[4:7], v[146:149], v[242:245], v[4:7]
	s_setprio 0
	s_setprio 1
	v_mfma_f32_16x16x32_bf16 v[100:103], v[150:153], v[166:169], v[100:103]
	v_mfma_f32_16x16x32_bf16 v[96:99], v[158:161], v[166:169], v[96:99]
	v_mfma_f32_16x16x32_bf16 v[92:95], v[150:153], v[174:177], v[92:95]
	v_mfma_f32_16x16x32_bf16 v[88:91], v[158:161], v[174:177], v[88:91]
	v_mfma_f32_16x16x32_bf16 v[84:87], v[150:153], v[230:233], v[84:87]
	v_mfma_f32_16x16x32_bf16 v[80:83], v[158:161], v[230:233], v[80:83]
	v_mfma_f32_16x16x32_bf16 v[76:79], v[150:153], v[238:241], v[76:79]
	v_mfma_f32_16x16x32_bf16 v[72:75], v[158:161], v[238:241], v[72:75]
	v_mfma_f32_16x16x32_bf16 v[100:103], v[154:157], v[170:173], v[100:103]
	v_mfma_f32_16x16x32_bf16 v[96:99], v[162:165], v[170:173], v[96:99]
	v_mfma_f32_16x16x32_bf16 v[92:95], v[154:157], v[178:181], v[92:95]
	v_mfma_f32_16x16x32_bf16 v[88:91], v[162:165], v[178:181], v[88:91]
	v_mfma_f32_16x16x32_bf16 v[84:87], v[154:157], v[234:237], v[84:87]
	v_mfma_f32_16x16x32_bf16 v[80:83], v[162:165], v[234:237], v[80:83]
	v_mfma_f32_16x16x32_bf16 v[76:79], v[154:157], v[242:245], v[76:79]
	v_mfma_f32_16x16x32_bf16 v[72:75], v[162:165], v[242:245], v[72:75]
	s_setprio 0
	s_barrier
	s_add_i32 s27, s27, s11
	v_lshl_add_u64 v[212:213], v[204:205], 0, v[192:193]
	s_mov_b32 m0, s27
	ds_read_b128 v[166:169], v227 offset:16384
	ds_read_b128 v[170:173], v227 offset:17408
	ds_read_b128 v[174:177], v227 offset:18432
	ds_read_b128 v[178:181], v227 offset:19456
	ds_read_b128 v[230:233], v227 offset:20480
	ds_read_b128 v[234:237], v227 offset:21504
	ds_read_b128 v[238:241], v227 offset:22528
	ds_read_b128 v[242:245], v227 offset:23552
	global_load_lds_dwordx4 v[212:213], off
	v_lshl_add_u64 v[218:219], v[204:205], 0, v[196:197]
	s_add_i32 m0, s27, 0x2000
	v_lshl_add_u64 v[204:205], v[204:205], 0, v[198:199]
	s_add_i32 s26, s26, s11
	global_load_lds_dwordx4 v[218:219], off
	v_lshl_add_u64 v[246:247], v[204:205], 0, v[192:193]
	s_mov_b32 m0, s26
	v_lshl_add_u64 v[204:205], v[204:205], 0, v[196:197]
	global_load_lds_dwordx4 v[246:247], off
	s_add_i32 m0, s26, 0x2000
	v_lshl_add_u64 v[248:249], s[8:9], 0, v[190:191]
	global_load_lds_dwordx4 v[204:205], off
	s_mov_b32 m0, s20
	v_lshl_add_u64 v[250:251], s[8:9], 0, v[194:195]
	global_load_lds_dwordx4 v[248:249], off
	s_mov_b32 m0, s48
	s_nop 0
	global_load_lds_dwordx4 v[250:251], off
	s_waitcnt vmcnt(8)
	s_waitcnt lgkmcnt(0)
	s_barrier
; #define PG8_STAGE(bufoff, gbase, voff) do { _Pragma("unroll") for (int _i = 0; _i < 2; ++_i) \
;         __builtin_amdgcn_global_load_lds((const unsigned*)((const char*)(gbase) + (voff)[_i]), (LAS unsigned*)(lds + (bufoff) + ldsw + _i * 8192), 16, 0, 0); } while (0)
; #define PG8_LDA(dst, b, h) do { _Pragma("unroll") for (int m = 0; m < 4; ++m) _Pragma("unroll") for (int k = 0; k < 2; ++k) dst[m][k] = *(const LAS bf16x8*)(lds + PG8_SA(b, h) + aoff + m * 2048 + k * 1024); } while (0)
; #define PG8_LDB(dst, b, h) do { _Pragma("unroll") for (int n = 0; n < 2; ++n) _Pragma("unroll") for (int k = 0; k < 2; ++k) dst[n][k] = *(const LAS bf16x8*)(lds + PG8_SB(b, h) + boff + n * 2048 + k * 1024); } while (0)
; #define PG8_MMA(ai, bj, At, Bt) do { __builtin_amdgcn_s_setprio(1); _Pragma("unroll") for (int m = 0; m < 4; ++m) _Pragma("unroll") for (int n = 0; n < 2; ++n) _Pragma("unroll") for (int k = 0; k < 2; ++k) \
;         acc[ai][bj][m][n] = __builtin_amdgcn_mfma_f32_16x16x32_bf16(Bt[n][k], At[m][k], acc[ai][bj][m][n], 0, 0, 0); __builtin_amdgcn_s_setprio(0); } while (0)
; #define PG8_WAIT_V(n) asm volatile("s_waitcnt vmcnt(" #n ")" ::: "memory")
; #define PG8_WAIT_L(n) asm volatile("s_waitcnt lgkmcnt(" #n ")" ::: "memory")
; #define PG8_BAR __builtin_amdgcn_s_barrier()
; #define PG8_SCHED __builtin_amdgcn_sched_barrier(0)
;     ...
;             PG8_WAIT_V(8); PG8_WAIT_L(0); PG8_BAR; PG8_MMA(1, 0, At, B0); PG8_MMA(1, 1, At, B1); PG8_BAR; PG8_SCHED;
;             PG8_LDB(B0, 1, 0); PG8_LDB(B1, 1, 1); PG8_SCHED; PG8_LDA(At, 1, 0); PG8_STAGE(PG8_SA(0, 1), a2 + hstepA, voffA);
;             PG8_WAIT_V(8); PG8_WAIT_L(0); PG8_BAR; PG8_MMA(0, 0, At, B0); PG8_MMA(0, 1, At, B1); PG8_BAR; PG8_SCHED;
	s_setprio 1
	s_waitcnt lgkmcnt(0)
	v_mfma_f32_16x16x32_bf16 v[68:71], v[134:137], v[166:169], v[68:71]
	v_mfma_f32_16x16x32_bf16 v[8:11], v[142:145], v[166:169], v[8:11]
	v_mfma_f32_16x16x32_bf16 v[64:67], v[134:137], v[174:177], v[64:67]
	v_mfma_f32_16x16x32_bf16 v[60:63], v[142:145], v[174:177], v[60:63]
	v_mfma_f32_16x16x32_bf16 v[56:59], v[134:137], v[230:233], v[56:59]
	v_mfma_f32_16x16x32_bf16 v[52:55], v[142:145], v[230:233], v[52:55]
	v_mfma_f32_16x16x32_bf16 v[48:51], v[134:137], v[238:241], v[48:51]
	v_mfma_f32_16x16x32_bf16 v[12:15], v[142:145], v[238:241], v[12:15]
	v_mfma_f32_16x16x32_bf16 v[68:71], v[138:141], v[170:173], v[68:71]
	v_mfma_f32_16x16x32_bf16 v[8:11], v[146:149], v[170:173], v[8:11]
	v_mfma_f32_16x16x32_bf16 v[64:67], v[138:141], v[178:181], v[64:67]
	v_mfma_f32_16x16x32_bf16 v[60:63], v[146:149], v[178:181], v[60:63]
	v_mfma_f32_16x16x32_bf16 v[56:59], v[138:141], v[234:237], v[56:59]
	v_mfma_f32_16x16x32_bf16 v[52:55], v[146:149], v[234:237], v[52:55]
	v_mfma_f32_16x16x32_bf16 v[48:51], v[138:141], v[242:245], v[48:51]
	v_mfma_f32_16x16x32_bf16 v[12:15], v[146:149], v[242:245], v[12:15]
	s_setprio 0
	s_setprio 1
	v_mfma_f32_16x16x32_bf16 v[44:47], v[150:153], v[166:169], v[44:47]
	v_mfma_f32_16x16x32_bf16 v[40:43], v[158:161], v[166:169], v[40:43]
	v_mfma_f32_16x16x32_bf16 v[36:39], v[150:153], v[174:177], v[36:39]
	v_mfma_f32_16x16x32_bf16 v[32:35], v[158:161], v[174:177], v[32:35]
	v_mfma_f32_16x16x32_bf16 v[28:31], v[150:153], v[230:233], v[28:31]
	v_mfma_f32_16x16x32_bf16 v[24:27], v[158:161], v[230:233], v[24:27]
	v_mfma_f32_16x16x32_bf16 v[20:23], v[150:153], v[238:241], v[20:23]
	v_mfma_f32_16x16x32_bf16 v[16:19], v[158:161], v[238:241], v[16:19]
	v_mfma_f32_16x16x32_bf16 v[44:47], v[154:157], v[170:173], v[44:47]
	v_mfma_f32_16x16x32_bf16 v[40:43], v[162:165], v[170:173], v[40:43]
	v_mfma_f32_16x16x32_bf16 v[36:39], v[154:157], v[178:181], v[36:39]
	v_mfma_f32_16x16x32_bf16 v[32:35], v[162:165], v[178:181], v[32:35]
	v_mfma_f32_16x16x32_bf16 v[28:31], v[154:157], v[234:237], v[28:31]
	v_mfma_f32_16x16x32_bf16 v[24:27], v[162:165], v[234:237], v[24:27]
	v_mfma_f32_16x16x32_bf16 v[20:23], v[154:157], v[242:245], v[20:23]
	v_mfma_f32_16x16x32_bf16 v[16:19], v[162:165], v[242:245], v[16:19]
	s_setprio 0
	s_barrier
	s_add_i32 s26, 0, 0x18000
	s_add_i32 s27, 0, 0x1c000
	v_add_u32_e32 v146, s26, v226
	v_add_u32_e32 v162, s27, v226
	ds_read_b128 v[134:137], v146
	ds_read_b128 v[138:141], v146 offset:1024
	ds_read_b128 v[142:145], v146 offset:2048
	ds_read_b128 v[146:149], v146 offset:3072
	ds_read_b128 v[150:153], v162
	ds_read_b128 v[154:157], v162 offset:1024
	ds_read_b128 v[158:161], v162 offset:2048
	ds_read_b128 v[162:165], v162 offset:3072
	s_add_u32 s8, s8, s10
	s_addc_u32 s9, s9, 0
	s_mov_b32 m0, s51
	v_lshl_add_u64 v[214:215], s[8:9], 0, v[190:191]
	ds_read_b128 v[166:169], v227 offset:32768
	ds_read_b128 v[170:173], v227 offset:33792
	ds_read_b128 v[174:177], v227 offset:34816
	ds_read_b128 v[178:181], v227 offset:35840
	ds_read_b128 v[230:233], v227 offset:36864
	ds_read_b128 v[234:237], v227 offset:37888
	ds_read_b128 v[238:241], v227 offset:38912
	ds_read_b128 v[242:245], v227 offset:39936
	global_load_lds_dwordx4 v[214:215], off
	v_lshl_add_u64 v[214:215], s[8:9], 0, v[194:195]
	s_mov_b32 m0, s62
	s_nop 0
	global_load_lds_dwordx4 v[214:215], off
	s_waitcnt vmcnt(8)
	s_waitcnt lgkmcnt(0)
	s_barrier
	s_setprio 1
	s_waitcnt lgkmcnt(0)
	v_mfma_f32_16x16x32_bf16 v[124:127], v[134:137], v[166:169], v[124:127]
	v_mfma_f32_16x16x32_bf16 v[0:3], v[142:145], v[166:169], v[0:3]
	v_mfma_f32_16x16x32_bf16 v[120:123], v[134:137], v[174:177], v[120:123]
	v_mfma_f32_16x16x32_bf16 v[116:119], v[142:145], v[174:177], v[116:119]
	v_mfma_f32_16x16x32_bf16 v[112:115], v[134:137], v[230:233], v[112:115]
	v_mfma_f32_16x16x32_bf16 v[108:111], v[142:145], v[230:233], v[108:111]
	v_mfma_f32_16x16x32_bf16 v[104:107], v[134:137], v[238:241], v[104:107]
	v_mfma_f32_16x16x32_bf16 v[4:7], v[142:145], v[238:241], v[4:7]
	v_mfma_f32_16x16x32_bf16 v[124:127], v[138:141], v[170:173], v[124:127]
	v_mfma_f32_16x16x32_bf16 v[0:3], v[146:149], v[170:173], v[0:3]
	v_mfma_f32_16x16x32_bf16 v[120:123], v[138:141], v[178:181], v[120:123]
	v_mfma_f32_16x16x32_bf16 v[116:119], v[146:149], v[178:181], v[116:119]
	v_mfma_f32_16x16x32_bf16 v[112:115], v[138:141], v[234:237], v[112:115]
	v_mfma_f32_16x16x32_bf16 v[108:111], v[146:149], v[234:237], v[108:111]
	v_mfma_f32_16x16x32_bf16 v[104:107], v[138:141], v[242:245], v[104:107]
	v_mfma_f32_16x16x32_bf16 v[4:7], v[146:149], v[242:245], v[4:7]
	s_setprio 0
	s_setprio 1
	v_mfma_f32_16x16x32_bf16 v[100:103], v[150:153], v[166:169], v[100:103]
	v_mfma_f32_16x16x32_bf16 v[96:99], v[158:161], v[166:169], v[96:99]
	v_mfma_f32_16x16x32_bf16 v[92:95], v[150:153], v[174:177], v[92:95]
	v_mfma_f32_16x16x32_bf16 v[88:91], v[158:161], v[174:177], v[88:91]
	v_mfma_f32_16x16x32_bf16 v[84:87], v[150:153], v[230:233], v[84:87]
	v_mfma_f32_16x16x32_bf16 v[80:83], v[158:161], v[230:233], v[80:83]
	v_mfma_f32_16x16x32_bf16 v[76:79], v[150:153], v[238:241], v[76:79]
	v_mfma_f32_16x16x32_bf16 v[72:75], v[158:161], v[238:241], v[72:75]
	v_mfma_f32_16x16x32_bf16 v[100:103], v[154:157], v[170:173], v[100:103]
	v_mfma_f32_16x16x32_bf16 v[96:99], v[162:165], v[170:173], v[96:99]
	v_mfma_f32_16x16x32_bf16 v[92:95], v[154:157], v[178:181], v[92:95]
	v_mfma_f32_16x16x32_bf16 v[88:91], v[162:165], v[178:181], v[88:91]
	v_mfma_f32_16x16x32_bf16 v[84:87], v[154:157], v[234:237], v[84:87]
	v_mfma_f32_16x16x32_bf16 v[80:83], v[162:165], v[234:237], v[80:83]
	v_mfma_f32_16x16x32_bf16 v[76:79], v[154:157], v[242:245], v[76:79]
	v_mfma_f32_16x16x32_bf16 v[72:75], v[162:165], v[242:245], v[72:75]
	s_setprio 0
	s_barrier
; #define PG8_STAGE(bufoff, gbase, voff) do { _Pragma("unroll") for (int _i = 0; _i < 2; ++_i) \
;         __builtin_amdgcn_global_load_lds((const unsigned*)((const char*)(gbase) + (voff)[_i]), (LAS unsigned*)(lds + (bufoff) + ldsw + _i * 8192), 16, 0, 0); } while (0)
; #define PG8_LDA(dst, b, h) do { _Pragma("unroll") for (int m = 0; m < 4; ++m) _Pragma("unroll") for (int k = 0; k < 2; ++k) dst[m][k] = *(const LAS bf16x8*)(lds + PG8_SA(b, h) + aoff + m * 2048 + k * 1024); } while (0)
; #define PG8_MMA(ai, bj, At, Bt) do { __builtin_amdgcn_s_setprio(1); _Pragma("unroll") for (int m = 0; m < 4; ++m) _Pragma("unroll") for (int n = 0; n < 2; ++n) _Pragma("unroll") for (int k = 0; k < 2; ++k) \
;         acc[ai][bj][m][n] = __builtin_amdgcn_mfma_f32_16x16x32_bf16(Bt[n][k], At[m][k], acc[ai][bj][m][n], 0, 0, 0); __builtin_amdgcn_s_setprio(0); } while (0)
; #define PG8_WAIT_V(n) asm volatile("s_waitcnt vmcnt(" #n ")" ::: "memory")
; #define PG8_WAIT_L(n) asm volatile("s_waitcnt lgkmcnt(" #n ")" ::: "memory")
; #define PG8_BAR __builtin_amdgcn_s_barrier()
; #define PG8_SCHED __builtin_amdgcn_sched_barrier(0)
;     ...
;             PG8_WAIT_V(8); PG8_WAIT_L(0); PG8_BAR; PG8_MMA(0, 0, At, B0); PG8_MMA(0, 1, At, B1); PG8_BAR; PG8_SCHED;
;             PG8_LDA(At, 1, 1); PG8_STAGE(PG8_SB(1, 0), b3, voffB); PG8_STAGE(PG8_SB(1, 1), b3 + hstepB, voffB); PG8_STAGE(PG8_SA(1, 0), a3, voffA);
;             PG8_WAIT_V(8); PG8_WAIT_L(0); PG8_BAR; PG8_MMA(1, 0, At, B0); PG8_MMA(1, 1, At, B1); PG8_BAR; PG8_SCHED;
;         }
;         if (wr == 0) PG8_BAR;
	s_add_i32 s8, s26, s11
	v_lshl_add_u64 v[212:213], v[212:213], 0, s[70:71]
	s_mov_b32 m0, s8
	ds_read_b128 v[166:169], v227 offset:49152
	ds_read_b128 v[170:173], v227 offset:50176
	ds_read_b128 v[174:177], v227 offset:51200
	ds_read_b128 v[178:181], v227 offset:52224
	ds_read_b128 v[230:233], v227 offset:53248
	ds_read_b128 v[234:237], v227 offset:54272
	ds_read_b128 v[238:241], v227 offset:55296
	ds_read_b128 v[242:245], v227 offset:56320
	global_load_lds_dwordx4 v[212:213], off
	v_lshl_add_u64 v[212:213], v[218:219], 0, s[70:71]
	s_add_i32 m0, s8, 0x2000
	s_add_i32 s8, s27, s11
	global_load_lds_dwordx4 v[212:213], off
	v_lshl_add_u64 v[212:213], v[246:247], 0, s[70:71]
	s_mov_b32 m0, s8
	v_lshl_add_u64 v[204:205], v[204:205], 0, s[70:71]
	global_load_lds_dwordx4 v[212:213], off
	s_add_i32 m0, s8, 0x2000
	s_nop 0
	global_load_lds_dwordx4 v[204:205], off
	v_lshl_add_u64 v[204:205], v[248:249], 0, s[70:71]
	s_mov_b32 m0, s65
	s_nop 0
	global_load_lds_dwordx4 v[204:205], off
	v_lshl_add_u64 v[204:205], v[250:251], 0, s[70:71]
	s_mov_b32 m0, s49
	s_nop 0
	global_load_lds_dwordx4 v[204:205], off
	s_waitcnt vmcnt(8)
	s_waitcnt lgkmcnt(0)
	s_barrier
	s_setprio 1
	s_waitcnt lgkmcnt(0)
	v_mfma_f32_16x16x32_bf16 v[68:71], v[134:137], v[166:169], v[68:71]
	v_mfma_f32_16x16x32_bf16 v[8:11], v[142:145], v[166:169], v[8:11]
	v_mfma_f32_16x16x32_bf16 v[64:67], v[134:137], v[174:177], v[64:67]
	v_mfma_f32_16x16x32_bf16 v[60:63], v[142:145], v[174:177], v[60:63]
	v_mfma_f32_16x16x32_bf16 v[56:59], v[134:137], v[230:233], v[56:59]
	v_mfma_f32_16x16x32_bf16 v[52:55], v[142:145], v[230:233], v[52:55]
	v_mfma_f32_16x16x32_bf16 v[48:51], v[134:137], v[238:241], v[48:51]
	v_mfma_f32_16x16x32_bf16 v[12:15], v[142:145], v[238:241], v[12:15]
	v_mfma_f32_16x16x32_bf16 v[68:71], v[138:141], v[170:173], v[68:71]
	v_mfma_f32_16x16x32_bf16 v[8:11], v[146:149], v[170:173], v[8:11]
	v_mfma_f32_16x16x32_bf16 v[64:67], v[138:141], v[178:181], v[64:67]
	v_mfma_f32_16x16x32_bf16 v[60:63], v[146:149], v[178:181], v[60:63]
	v_mfma_f32_16x16x32_bf16 v[56:59], v[138:141], v[234:237], v[56:59]
	v_mfma_f32_16x16x32_bf16 v[52:55], v[146:149], v[234:237], v[52:55]
	v_mfma_f32_16x16x32_bf16 v[48:51], v[138:141], v[242:245], v[48:51]
	v_mfma_f32_16x16x32_bf16 v[12:15], v[146:149], v[242:245], v[12:15]
	s_setprio 0
	s_setprio 1
	v_mfma_f32_16x16x32_bf16 v[44:47], v[150:153], v[166:169], v[44:47]
	v_mfma_f32_16x16x32_bf16 v[40:43], v[158:161], v[166:169], v[40:43]
	v_mfma_f32_16x16x32_bf16 v[36:39], v[150:153], v[174:177], v[36:39]
	v_mfma_f32_16x16x32_bf16 v[32:35], v[158:161], v[174:177], v[32:35]
	v_mfma_f32_16x16x32_bf16 v[28:31], v[150:153], v[230:233], v[28:31]
	v_mfma_f32_16x16x32_bf16 v[24:27], v[158:161], v[230:233], v[24:27]
	v_mfma_f32_16x16x32_bf16 v[20:23], v[150:153], v[238:241], v[20:23]
	v_mfma_f32_16x16x32_bf16 v[16:19], v[158:161], v[238:241], v[16:19]
	v_mfma_f32_16x16x32_bf16 v[44:47], v[154:157], v[170:173], v[44:47]
	v_mfma_f32_16x16x32_bf16 v[40:43], v[162:165], v[170:173], v[40:43]
	v_mfma_f32_16x16x32_bf16 v[36:39], v[154:157], v[178:181], v[36:39]
	v_mfma_f32_16x16x32_bf16 v[32:35], v[162:165], v[178:181], v[32:35]
	v_mfma_f32_16x16x32_bf16 v[28:31], v[154:157], v[234:237], v[28:31]
	v_mfma_f32_16x16x32_bf16 v[24:27], v[162:165], v[234:237], v[24:27]
	v_mfma_f32_16x16x32_bf16 v[20:23], v[154:157], v[242:245], v[20:23]
	v_mfma_f32_16x16x32_bf16 v[16:19], v[162:165], v[242:245], v[16:19]
	s_setprio 0
	s_barrier
	s_add_u32 s0, s0, 0x100
	s_addc_u32 s1, s1, 0
	v_lshl_add_u64 v[130:131], v[130:131], 0, s[94:95]
	v_lshl_add_u64 v[128:129], v[128:129], 0, s[94:95]
	s_cmp_ge_u32 s38, s52
	s_mov_b32 s8, s38
	s_cbranch_scc0 .LBB0_159
	v_readlane_b32 s0, v254, 50
	v_readlane_b32 s1, v254, 51
	s_and_b64 vcc, exec, s[0:1]
	s_movk_i32 s67, 0xfe
	s_cbranch_vccz .LBB0_162
	s_barrier

;     ...
;         const bool has_next = S.next(ui + 1, nxt);
;         const char* nA = has_next ? nxt.A : cA; const char* nB = has_next ? nxt.B : cB;
;         for (int t = 0; t < nt; t += 2) {
;             const bool last = (t == nt - 2);
;             const char* a1 = cA + (size_t)(t + 1) * kstep;
;             const char* a2 = last ? nA : cA + (size_t)(t + 2) * kstep; const char* b2 = last ? nB : cB + (size_t)(t + 2) * kstep;
.LBB0_317:
	s_mov_b64 s[54:55], s[68:69]
	v_mov_b32_e32 v189, v128
	s_xor_b64 s[66:67], s[64:65], -1
	v_mov_b32_e32 v128, s55
	s_mov_b64 s[36:37], s[38:39]
	s_and_b64 s[0:1], s[64:65], exec
	v_cndmask_b32_e64 v132, v161, v128, s[64:65]
	v_mov_b32_e32 v128, s54
	s_mov_b64 s[6:7], s[56:57]
	s_mov_b64 s[14:15], s[58:59]
	s_mov_b32 s26, s19
	s_cselect_b32 s13, s37, s3
	s_cselect_b32 s56, s36, s2
	v_cndmask_b32_e64 v133, v160, v128, s[64:65]
	s_mov_b32 s38, 0
	s_mov_b64 s[0:1], 0x100
	v_mov_b64_e32 v[128:129], v[172:173]
	v_mov_b64_e32 v[130:131], v[170:171]
	s_nop 0
	s_nop 0
	s_nop 0
	s_nop 0
